# grid barrier: the XCD leader no longer waits for its own XCD-generation atomic to complete before rejoining its workgroup barrier
# baseline (speedup 1.0000x reference)
.LBB0_857:
	s_or_b64 exec, exec, s[28:29]
.LBB0_858:
	s_or_b64 exec, exec, s[4:5]
	s_waitcnt lgkmcnt(0)
	s_barrier
	s_getpc_b64 s[98:99]
